# v57 + P4a: all 26 global loads of the forget-gate chunk issued up front (one round trip instead of four dependent ones)
# baseline (speedup 1.0000x reference)
.LBB0_351:
	global_load_dword v162, v1, s[42:43]
	global_load_dword v163, v1, s[42:43] offset:4
	v_add_u32_e32 v10, s15, v171
	v_ashrrev_i32_e32 v11, 31, v10
	s_mov_b64 s[68:69], 0x8000
	v_lshlrev_b64 v[154:155], 11, v[10:11]
	v_lshl_add_u64 v[154:155], v[4:5], 0, v[154:155]
	global_load_dwordx4 v[138:141], v[2:3], off
	global_load_dwordx4 v[74:77], v[154:155], off
	v_lshl_add_u64 v[156:157], v[154:155], 0, s[68:69]
	v_lshl_add_u64 v[158:159], v[156:157], 0, s[68:69]
	v_lshl_add_u64 v[160:161], v[158:159], 0, s[68:69]
	global_load_dwordx4 v[78:81], v[156:157], off
	global_load_dwordx4 v[82:85], v[158:159], off
	global_load_dwordx4 v[86:89], v[160:161], off
	global_load_dwordx4 v[142:145], v[2:3], off offset:64
	global_load_dwordx4 v[90:93], v[154:155], off offset:64
	global_load_dwordx4 v[94:97], v[156:157], off offset:64
	global_load_dwordx4 v[98:101], v[158:159], off offset:64
	global_load_dwordx4 v[102:105], v[160:161], off offset:64
	global_load_dwordx4 v[146:149], v[2:3], off offset:128
	global_load_dwordx4 v[106:109], v[154:155], off offset:128
	global_load_dwordx4 v[110:113], v[156:157], off offset:128
	global_load_dwordx4 v[114:117], v[158:159], off offset:128
	global_load_dwordx4 v[118:121], v[160:161], off offset:128
	global_load_dwordx4 v[150:153], v[2:3], off offset:192
	global_load_dwordx4 v[122:125], v[154:155], off offset:192
	global_load_dwordx4 v[126:129], v[156:157], off offset:192
	global_load_dwordx4 v[130:133], v[158:159], off offset:192
	global_load_dwordx4 v[134:137], v[160:161], off offset:192
	v_add_u32_e32 v10, s15, v204
	v_ashrrev_i32_e32 v11, 31, v10
	v_lshlrev_b64 v[50:51], 6, v[10:11]
	v_lshl_add_u64 v[66:67], s[60:61], 0, v[50:51]
	global_load_dwordx4 v[50:53], v[66:67], off
	global_load_dwordx4 v[54:57], v[66:67], off offset:16
	global_load_dwordx4 v[62:65], v[66:67], off offset:32
	global_load_dwordx4 v[58:61], v[66:67], off offset:48
	v_lshl_add_u64 v[10:11], v[10:11], 2, s[38:39]
	s_waitcnt vmcnt(22)
	v_mfma_f32_16x16x32_bf16 v[30:33], v[74:77], v[138:141], 0
	s_waitcnt vmcnt(21)
	v_mfma_f32_16x16x32_bf16 v[34:37], v[78:81], v[138:141], 0
	s_waitcnt vmcnt(20)
	v_mfma_f32_16x16x32_bf16 v[38:41], v[82:85], v[138:141], 0
	s_waitcnt vmcnt(19)
	v_mfma_f32_16x16x32_bf16 v[26:29], v[86:89], v[138:141], 0
	s_waitcnt vmcnt(17)
	v_mfma_f32_16x16x32_bf16 v[30:33], v[90:93], v[142:145], v[30:33]
	s_waitcnt vmcnt(16)
	v_mfma_f32_16x16x32_bf16 v[34:37], v[94:97], v[142:145], v[34:37]
	s_waitcnt vmcnt(15)
	v_mfma_f32_16x16x32_bf16 v[38:41], v[98:101], v[142:145], v[38:41]
	s_waitcnt vmcnt(14)
	v_mfma_f32_16x16x32_bf16 v[26:29], v[102:105], v[142:145], v[26:29]
	s_waitcnt vmcnt(12)
	v_mfma_f32_16x16x32_bf16 v[30:33], v[106:109], v[146:149], v[30:33]
	s_waitcnt vmcnt(11)
	v_mfma_f32_16x16x32_bf16 v[34:37], v[110:113], v[146:149], v[34:37]
	s_waitcnt vmcnt(10)
	v_mfma_f32_16x16x32_bf16 v[38:41], v[114:117], v[146:149], v[38:41]
	s_waitcnt vmcnt(9)
	v_mfma_f32_16x16x32_bf16 v[26:29], v[118:121], v[146:149], v[26:29]
	s_waitcnt vmcnt(7)
	v_mfma_f32_16x16x32_bf16 v[30:33], v[122:125], v[150:153], v[30:33]
	s_waitcnt vmcnt(6)
	v_mfma_f32_16x16x32_bf16 v[34:37], v[126:129], v[150:153], v[34:37]
	s_waitcnt vmcnt(5)
	v_mfma_f32_16x16x32_bf16 v[38:41], v[130:133], v[150:153], v[38:41]
	s_waitcnt vmcnt(4)
	v_mfma_f32_16x16x32_bf16 v[26:29], v[134:137], v[150:153], v[26:29]
	s_waitcnt vmcnt(0)
	v_add_f32_e32 v25, v50, v51
	s_nop 15
	s_nop 3
	ds_write2_b32 v19, v30, v31 offset1:16
	ds_write2_b32 v19, v32, v33 offset0:32 offset1:48
	s_nop 1
	ds_write2_b32 v22, v34, v35 offset1:16
	ds_write2_b32 v22, v36, v37 offset0:32 offset1:48
	s_nop 0
	ds_write2_b32 v23, v38, v39 offset1:16
	ds_write2_b32 v23, v40, v41 offset0:32 offset1:48
	ds_write2_b32 v24, v26, v27 offset1:16
	ds_write2_b32 v24, v28, v29 offset0:32 offset1:48
	s_waitcnt lgkmcnt(0)
	s_barrier
	v_mov_b32_e32 v34, v162
	v_add_f32_e32 v26, v52, v53
	v_add_f32_e32 v25, v25, v26
	s_waitcnt vmcnt(3)
	v_add_f32_e32 v27, v54, v55
	v_add_f32_e32 v28, v56, v57
	s_waitcnt vmcnt(2)
	v_add_f32_e32 v29, v62, v63
	v_add_f32_e32 v30, v64, v65
	v_add_f32_e32 v26, v27, v28
	s_waitcnt vmcnt(1)
	v_add_f32_e32 v31, v58, v59
	v_add_f32_e32 v32, v60, v61
	v_add_f32_e32 v27, v29, v30
	v_add_f32_e32 v25, v25, v26
	v_add_f32_e32 v28, v31, v32
	v_add_f32_e32 v25, v25, v27
	v_add_f32_e32 v25, v25, v28
	v_fmamk_f32 v25, v25, 0x3a800000, v20
	v_mul_f32_e32 v26, 0x4f800000, v25
	v_cmp_gt_f32_e32 vcc, s57, v25
	s_nop 1
	v_cndmask_b32_e32 v25, v25, v26, vcc
	v_sqrt_f32_e32 v26, v25
	s_nop 0
	v_add_u32_e32 v27, -1, v26
	v_add_u32_e32 v28, 1, v26
	v_fma_f32 v29, -v27, v26, v25
	v_fma_f32 v30, -v28, v26, v25
	v_cmp_ge_f32_e64 s[22:23], 0, v29
	s_nop 1
	v_cndmask_b32_e64 v26, v26, v27, s[22:23]
	v_cmp_lt_f32_e64 s[22:23], 0, v30
	s_nop 1
	v_cndmask_b32_e64 v26, v26, v28, s[22:23]
	v_mul_f32_e32 v27, 0x37800000, v26
	v_cndmask_b32_e32 v26, v26, v27, vcc
	v_cmp_class_f32_e32 vcc, v25, v21
	s_nop 1
	v_cndmask_b32_e32 v25, v26, v25, vcc
	v_div_scale_f32 v35, s[22:23], v25, v25, 1.0
	v_rcp_f32_e32 v37, v35
	ds_read2st64_b32 v[26:27], v12 offset1:16
	ds_read2st64_b32 v[28:29], v12 offset0:32 offset1:48
	ds_read2st64_b32 v[30:31], v12 offset0:64 offset1:80
	ds_read2st64_b32 v[32:33], v12 offset0:96 offset1:112
	v_div_scale_f32 v36, vcc, 1.0, v25, 1.0
	v_fma_f32 v38, -v35, v37, 1.0
	s_waitcnt lgkmcnt(3)
	v_add_f32_e32 v26, 0, v26
	v_fmac_f32_e32 v37, v38, v37
	v_add_f32_e32 v26, v26, v27
	v_mul_f32_e32 v38, v36, v37
	s_waitcnt lgkmcnt(2)
	v_add_f32_e32 v26, v26, v28
	v_fma_f32 v39, -v35, v38, v36
	v_add_f32_e32 v26, v26, v29
	v_fmac_f32_e32 v38, v39, v37
	s_waitcnt lgkmcnt(1)
	v_add_f32_e32 v26, v26, v30
	v_fma_f32 v27, -v35, v38, v36
	v_add_f32_e32 v26, v26, v31
	v_div_fmas_f32 v27, v27, v37, v38
	s_waitcnt lgkmcnt(0)
	v_add_f32_e32 v26, v26, v32
	v_div_fixup_f32 v25, v27, v25, 1.0
	v_add_f32_e32 v26, v26, v33
	s_waitcnt vmcnt(0)
	v_fmac_f32_e32 v34, v25, v26
	v_mul_f32_e64 v26, |v34|, s64
	v_exp_f32_e32 v26, v26
	v_min_f32_e32 v27, 0, v34
	v_lshl_add_u64 v[28:29], v[10:11], 0, s[46:47]
	v_add_f32_e32 v26, 1.0, v26
	v_log_f32_e32 v26, v26
	s_nop 0
	v_fmac_f32_e32 v27, 0xbf317218, v26
	s_nop 1
	v_add_f32_dpp v27, v27, v27 row_shr:1 row_mask:0xf bank_mask:0xf
	s_nop 1
	v_add_f32_dpp v27, v27, v27 row_shr:2 row_mask:0xf bank_mask:0xf
	s_nop 1
	v_add_f32_dpp v27, v27, v27 row_shr:4 row_mask:0xf bank_mask:0xf
	s_nop 1
	v_add_f32_dpp v27, v27, v27 row_shr:8 row_mask:0xf bank_mask:0xf
	s_nop 1
	v_add_f32_dpp v27, v27, v27 row_bcast:15 row_mask:0xa bank_mask:0xf
	s_nop 1
	v_add_f32_dpp v27, v27, v27 row_bcast:31 row_mask:0xc bank_mask:0xf
	v_mov_b32_e32 v26, v27
	global_store_dword v[28:29], v27, off sc1
	s_and_saveexec_b64 s[22:23], s[0:1]
	s_cbranch_execz .LBB0_353
	s_add_i32 s44, s14, s65
	s_ashr_i32 s45, s44, 31
	s_lshl_b64 s[44:45], s[44:45], 2
	s_add_u32 s44, s74, s44
	s_addc_u32 s45, s75, s45
	global_store_dword v1, v26, s[44:45] sc1
.LBB0_353:
	s_or_b64 exec, exec, s[22:23]
	v_mov_b32_e32 v34, v163
	v_add_u32_e32 v32, 4, v12
	ds_read2st64_b32 v[26:27], v32 offset1:16
	ds_read2st64_b32 v[28:29], v32 offset0:32 offset1:48
	ds_read2st64_b32 v[30:31], v32 offset0:64 offset1:80
	ds_read2st64_b32 v[32:33], v32 offset0:96 offset1:112
	v_lshl_add_u64 v[10:11], v[10:11], 0, s[48:49]
	s_waitcnt lgkmcnt(3)
	v_add_f32_e32 v26, 0, v26
	v_add_f32_e32 v26, v26, v27
	s_waitcnt lgkmcnt(2)
	v_add_f32_e32 v26, v26, v28
	v_add_f32_e32 v26, v26, v29
	s_waitcnt lgkmcnt(1)
	v_add_f32_e32 v26, v26, v30
	v_add_f32_e32 v26, v26, v31
	s_waitcnt lgkmcnt(0)
	v_add_f32_e32 v26, v26, v32
	v_add_f32_e32 v26, v26, v33
	v_fmac_f32_e32 v34, v25, v26
	v_mul_f32_e64 v25, |v34|, s64
	v_exp_f32_e32 v25, v25
	v_min_f32_e32 v26, 0, v34
	v_add_f32_e32 v25, 1.0, v25
	v_log_f32_e32 v25, v25
	s_nop 0
	v_fmac_f32_e32 v26, 0xbf317218, v25
	s_nop 1
	v_add_f32_dpp v26, v26, v26 row_shr:1 row_mask:0xf bank_mask:0xf
	s_nop 1
	v_add_f32_dpp v26, v26, v26 row_shr:2 row_mask:0xf bank_mask:0xf
	s_nop 1
	v_add_f32_dpp v26, v26, v26 row_shr:4 row_mask:0xf bank_mask:0xf
	s_nop 1
	v_add_f32_dpp v26, v26, v26 row_shr:8 row_mask:0xf bank_mask:0xf
	s_nop 1
	v_add_f32_dpp v26, v26, v26 row_bcast:15 row_mask:0xa bank_mask:0xf
	s_nop 1
	v_add_f32_dpp v26, v26, v26 row_bcast:31 row_mask:0xc bank_mask:0xf
	v_mov_b32_e32 v25, v26
	global_store_dword v[10:11], v26, off sc1
	s_and_saveexec_b64 s[22:23], s[0:1]
	s_cbranch_execz .LBB0_350
	s_add_i32 s33, s14, s65
	s_add_i32 s44, s33, 0x100
	s_ashr_i32 s45, s44, 31
	s_lshl_b64 s[44:45], s[44:45], 2
	s_add_u32 s44, s74, s44
	s_addc_u32 s45, s75, s45
	global_store_dword v1, v25, s[44:45] sc1
	s_branch .LBB0_350

.LBB0_443:
	global_load_dword v162, v1, s[40:41]
	global_load_dword v163, v1, s[40:41] offset:4
	v_add_u32_e32 v10, s15, v171
	v_ashrrev_i32_e32 v11, 31, v10
	s_mov_b64 s[68:69], 0x8000
	v_lshlrev_b64 v[154:155], 11, v[10:11]
	v_lshl_add_u64 v[154:155], v[4:5], 0, v[154:155]
	global_load_dwordx4 v[138:141], v[2:3], off
	global_load_dwordx4 v[74:77], v[154:155], off
	v_lshl_add_u64 v[156:157], v[154:155], 0, s[68:69]
	v_lshl_add_u64 v[158:159], v[156:157], 0, s[68:69]
	v_lshl_add_u64 v[160:161], v[158:159], 0, s[68:69]
	global_load_dwordx4 v[78:81], v[156:157], off
	global_load_dwordx4 v[82:85], v[158:159], off
	global_load_dwordx4 v[86:89], v[160:161], off
	global_load_dwordx4 v[142:145], v[2:3], off offset:64
	global_load_dwordx4 v[90:93], v[154:155], off offset:64
	global_load_dwordx4 v[94:97], v[156:157], off offset:64
	global_load_dwordx4 v[98:101], v[158:159], off offset:64
	global_load_dwordx4 v[102:105], v[160:161], off offset:64
	global_load_dwordx4 v[146:149], v[2:3], off offset:128
	global_load_dwordx4 v[106:109], v[154:155], off offset:128
	global_load_dwordx4 v[110:113], v[156:157], off offset:128
	global_load_dwordx4 v[114:117], v[158:159], off offset:128
	global_load_dwordx4 v[118:121], v[160:161], off offset:128
	global_load_dwordx4 v[150:153], v[2:3], off offset:192
	global_load_dwordx4 v[122:125], v[154:155], off offset:192
	global_load_dwordx4 v[126:129], v[156:157], off offset:192
	global_load_dwordx4 v[130:133], v[158:159], off offset:192
	global_load_dwordx4 v[134:137], v[160:161], off offset:192
	v_add_u32_e32 v10, s15, v204
	v_ashrrev_i32_e32 v11, 31, v10
	v_lshlrev_b64 v[50:51], 6, v[10:11]
	v_lshl_add_u64 v[66:67], s[60:61], 0, v[50:51]
	global_load_dwordx4 v[50:53], v[66:67], off
	global_load_dwordx4 v[54:57], v[66:67], off offset:16
	global_load_dwordx4 v[62:65], v[66:67], off offset:32
	global_load_dwordx4 v[58:61], v[66:67], off offset:48
	v_lshl_add_u64 v[10:11], v[10:11], 2, s[38:39]
	s_waitcnt vmcnt(22)
	v_mfma_f32_16x16x32_bf16 v[30:33], v[74:77], v[138:141], 0
	s_waitcnt vmcnt(21)
	v_mfma_f32_16x16x32_bf16 v[34:37], v[78:81], v[138:141], 0
	s_waitcnt vmcnt(20)
	v_mfma_f32_16x16x32_bf16 v[38:41], v[82:85], v[138:141], 0
	s_waitcnt vmcnt(19)
	v_mfma_f32_16x16x32_bf16 v[26:29], v[86:89], v[138:141], 0
	s_waitcnt vmcnt(17)
	v_mfma_f32_16x16x32_bf16 v[30:33], v[90:93], v[142:145], v[30:33]
	s_waitcnt vmcnt(16)
	v_mfma_f32_16x16x32_bf16 v[34:37], v[94:97], v[142:145], v[34:37]
	s_waitcnt vmcnt(15)
	v_mfma_f32_16x16x32_bf16 v[38:41], v[98:101], v[142:145], v[38:41]
	s_waitcnt vmcnt(14)
	v_mfma_f32_16x16x32_bf16 v[26:29], v[102:105], v[142:145], v[26:29]
	s_waitcnt vmcnt(12)
	v_mfma_f32_16x16x32_bf16 v[30:33], v[106:109], v[146:149], v[30:33]
	s_waitcnt vmcnt(11)
	v_mfma_f32_16x16x32_bf16 v[34:37], v[110:113], v[146:149], v[34:37]
	s_waitcnt vmcnt(10)
	v_mfma_f32_16x16x32_bf16 v[38:41], v[114:117], v[146:149], v[38:41]
	s_waitcnt vmcnt(9)
	v_mfma_f32_16x16x32_bf16 v[26:29], v[118:121], v[146:149], v[26:29]
	s_waitcnt vmcnt(7)
	v_mfma_f32_16x16x32_bf16 v[30:33], v[122:125], v[150:153], v[30:33]
	s_waitcnt vmcnt(6)
	v_mfma_f32_16x16x32_bf16 v[34:37], v[126:129], v[150:153], v[34:37]
	s_waitcnt vmcnt(5)
	v_mfma_f32_16x16x32_bf16 v[38:41], v[130:133], v[150:153], v[38:41]
	s_waitcnt vmcnt(4)
	v_mfma_f32_16x16x32_bf16 v[26:29], v[134:137], v[150:153], v[26:29]
	s_waitcnt vmcnt(0)
	v_add_f32_e32 v25, v50, v51
	s_nop 15
	s_nop 3
	ds_write2_b32 v19, v30, v31 offset1:16
	ds_write2_b32 v19, v32, v33 offset0:32 offset1:48
	s_nop 1
	ds_write2_b32 v22, v34, v35 offset1:16
	ds_write2_b32 v22, v36, v37 offset0:32 offset1:48
	s_nop 0
	ds_write2_b32 v23, v38, v39 offset1:16
	ds_write2_b32 v23, v40, v41 offset0:32 offset1:48
	ds_write2_b32 v24, v26, v27 offset1:16
	ds_write2_b32 v24, v28, v29 offset0:32 offset1:48
	s_waitcnt lgkmcnt(0)
	s_barrier
	v_mov_b32_e32 v34, v162
	v_add_f32_e32 v26, v52, v53
	v_add_f32_e32 v25, v25, v26
	s_waitcnt vmcnt(3)
	v_add_f32_e32 v27, v54, v55
	v_add_f32_e32 v28, v56, v57
	s_waitcnt vmcnt(2)
	v_add_f32_e32 v29, v62, v63
	v_add_f32_e32 v30, v64, v65
	v_add_f32_e32 v26, v27, v28
	s_waitcnt vmcnt(1)
	v_add_f32_e32 v31, v58, v59
	v_add_f32_e32 v32, v60, v61
	v_add_f32_e32 v27, v29, v30
	v_add_f32_e32 v25, v25, v26
	v_add_f32_e32 v28, v31, v32
	v_add_f32_e32 v25, v25, v27
	v_add_f32_e32 v25, v25, v28
	v_fmamk_f32 v25, v25, 0x3a800000, v20
	v_mul_f32_e32 v26, 0x4f800000, v25
	v_cmp_gt_f32_e32 vcc, s57, v25
	s_nop 1
	v_cndmask_b32_e32 v25, v25, v26, vcc
	v_sqrt_f32_e32 v26, v25
	s_nop 0
	v_add_u32_e32 v27, -1, v26
	v_add_u32_e32 v28, 1, v26
	v_fma_f32 v29, -v27, v26, v25
	v_fma_f32 v30, -v28, v26, v25
	v_cmp_ge_f32_e64 s[22:23], 0, v29
	s_nop 1
	v_cndmask_b32_e64 v26, v26, v27, s[22:23]
	v_cmp_lt_f32_e64 s[22:23], 0, v30
	s_nop 1
	v_cndmask_b32_e64 v26, v26, v28, s[22:23]
	v_mul_f32_e32 v27, 0x37800000, v26
	v_cndmask_b32_e32 v26, v26, v27, vcc
	v_cmp_class_f32_e32 vcc, v25, v21
	s_nop 1
	v_cndmask_b32_e32 v25, v26, v25, vcc
	v_div_scale_f32 v35, s[22:23], v25, v25, 1.0
	v_rcp_f32_e32 v37, v35
	ds_read2st64_b32 v[26:27], v12 offset1:16
	ds_read2st64_b32 v[28:29], v12 offset0:32 offset1:48
	ds_read2st64_b32 v[30:31], v12 offset0:64 offset1:80
	ds_read2st64_b32 v[32:33], v12 offset0:96 offset1:112
	v_div_scale_f32 v36, vcc, 1.0, v25, 1.0
	v_fma_f32 v38, -v35, v37, 1.0
	s_waitcnt lgkmcnt(3)
	v_add_f32_e32 v26, 0, v26
	v_fmac_f32_e32 v37, v38, v37
	v_add_f32_e32 v26, v26, v27
	v_mul_f32_e32 v38, v36, v37
	s_waitcnt lgkmcnt(2)
	v_add_f32_e32 v26, v26, v28
	v_fma_f32 v39, -v35, v38, v36
	v_add_f32_e32 v26, v26, v29
	v_fmac_f32_e32 v38, v39, v37
	s_waitcnt lgkmcnt(1)
	v_add_f32_e32 v26, v26, v30
	v_fma_f32 v27, -v35, v38, v36
	v_add_f32_e32 v26, v26, v31
	v_div_fmas_f32 v27, v27, v37, v38
	s_waitcnt lgkmcnt(0)
	v_add_f32_e32 v26, v26, v32
	v_div_fixup_f32 v25, v27, v25, 1.0
	v_add_f32_e32 v26, v26, v33
	s_waitcnt vmcnt(0)
	v_fmac_f32_e32 v34, v25, v26
	v_mul_f32_e64 v26, |v34|, s64
	v_exp_f32_e32 v26, v26
	v_min_f32_e32 v27, 0, v34
	v_lshl_add_u64 v[28:29], v[10:11], 0, s[58:59]
	v_add_f32_e32 v26, 1.0, v26
	v_log_f32_e32 v26, v26
	s_nop 0
	v_fmac_f32_e32 v27, 0xbf317218, v26
	s_nop 1
	v_add_f32_dpp v27, v27, v27 row_shr:1 row_mask:0xf bank_mask:0xf
	s_nop 1
	v_add_f32_dpp v27, v27, v27 row_shr:2 row_mask:0xf bank_mask:0xf
	s_nop 1
	v_add_f32_dpp v27, v27, v27 row_shr:4 row_mask:0xf bank_mask:0xf
	s_nop 1
	v_add_f32_dpp v27, v27, v27 row_shr:8 row_mask:0xf bank_mask:0xf
	s_nop 1
	v_add_f32_dpp v27, v27, v27 row_bcast:15 row_mask:0xa bank_mask:0xf
	s_nop 1
	v_add_f32_dpp v27, v27, v27 row_bcast:31 row_mask:0xc bank_mask:0xf
	v_mov_b32_e32 v26, v27
	global_store_dword v[28:29], v27, off sc1
	s_and_saveexec_b64 s[22:23], s[0:1]
	s_cbranch_execz .LBB0_445
	s_add_i32 s66, s14, s65
	s_ashr_i32 s67, s66, 31
	s_lshl_b64 s[66:67], s[66:67], 2
	s_add_u32 s66, s74, s66
	s_addc_u32 s67, s75, s67
	global_store_dword v1, v26, s[66:67] sc1
.LBB0_445:
	s_or_b64 exec, exec, s[22:23]
	v_mov_b32_e32 v34, v163
	v_add_u32_e32 v32, 4, v12
	ds_read2st64_b32 v[26:27], v32 offset1:16
	ds_read2st64_b32 v[28:29], v32 offset0:32 offset1:48
	ds_read2st64_b32 v[30:31], v32 offset0:64 offset1:80
	ds_read2st64_b32 v[32:33], v32 offset0:96 offset1:112
	v_lshl_add_u64 v[10:11], v[10:11], 0, s[62:63]
	s_waitcnt lgkmcnt(3)
	v_add_f32_e32 v26, 0, v26
	v_add_f32_e32 v26, v26, v27
	s_waitcnt lgkmcnt(2)
	v_add_f32_e32 v26, v26, v28
	v_add_f32_e32 v26, v26, v29
	s_waitcnt lgkmcnt(1)
	v_add_f32_e32 v26, v26, v30
	v_add_f32_e32 v26, v26, v31
	s_waitcnt lgkmcnt(0)
	v_add_f32_e32 v26, v26, v32
	v_add_f32_e32 v26, v26, v33
	v_fmac_f32_e32 v34, v25, v26
	v_mul_f32_e64 v25, |v34|, s64
	v_exp_f32_e32 v25, v25
	v_min_f32_e32 v26, 0, v34
	v_add_f32_e32 v25, 1.0, v25
	v_log_f32_e32 v25, v25
	s_nop 0
	v_fmac_f32_e32 v26, 0xbf317218, v25
	s_nop 1
	v_add_f32_dpp v26, v26, v26 row_shr:1 row_mask:0xf bank_mask:0xf
	s_nop 1
	v_add_f32_dpp v26, v26, v26 row_shr:2 row_mask:0xf bank_mask:0xf
	s_nop 1
	v_add_f32_dpp v26, v26, v26 row_shr:4 row_mask:0xf bank_mask:0xf
	s_nop 1
	v_add_f32_dpp v26, v26, v26 row_shr:8 row_mask:0xf bank_mask:0xf
	s_nop 1
	v_add_f32_dpp v26, v26, v26 row_bcast:15 row_mask:0xa bank_mask:0xf
	s_nop 1
	v_add_f32_dpp v26, v26, v26 row_bcast:31 row_mask:0xc bank_mask:0xf
	v_mov_b32_e32 v25, v26
	global_store_dword v[10:11], v26, off sc1
	s_and_saveexec_b64 s[22:23], s[0:1]
	s_cbranch_execz .LBB0_442
	s_add_i32 s33, s14, s65
	s_add_i32 s66, s33, 0x100
	s_ashr_i32 s67, s66, 31
	s_lshl_b64 s[66:67], s[66:67], 2
	s_add_u32 s66, s74, s66
	s_addc_u32 s67, s75, s67
	global_store_dword v1, v25, s[66:67] sc1
	s_branch .LBB0_442
